# out-proj fused epilogue: x residual loads of row groups 4..7 batched (no warm-up)
# speedup vs baseline: 1.0030x; 1.0030x over previous
.LBB0_228:
	s_lshl_b32 s2, s38, 5
	s_lshl_b32 s3, s18, 8
	s_or_b32 s2, s3, s2
	v_lshrrev_b32_e32 v122, 2, v210
	s_lshl_b32 s30, s29, 8
	v_and_or_b32 v214, v122, 12, s2
	s_add_i32 s2, s30, s28
	v_or_b32_e32 v122, s2, v219
	v_ashrrev_i32_e32 v215, 31, v214
	v_lshlrev_b64 v[124:125], 2, v[214:215]
	v_ashrrev_i32_e32 v123, 31, v122
	v_lshl_add_u64 v[216:217], s[0:1], 0, v[124:125]
	v_lshlrev_b64 v[130:131], 12, v[122:123]
	v_lshl_add_u64 v[130:131], v[216:217], 0, v[130:131]
	s_barrier
	global_load_dwordx4 v[206:209], v[130:131], off
	global_load_dwordx4 v[202:205], v[130:131], off offset:64
	global_load_dwordx4 v[198:201], v[130:131], off offset:512
	global_load_dwordx4 v[194:197], v[130:131], off offset:576
	v_or_b32_e32 v130, 16, v122
	v_ashrrev_i32_e32 v131, 31, v130
	v_lshlrev_b64 v[130:131], 12, v[130:131]
	v_lshl_add_u64 v[130:131], v[216:217], 0, v[130:131]
	global_load_dwordx4 v[190:193], v[130:131], off
	global_load_dwordx4 v[186:189], v[130:131], off offset:64
	global_load_dwordx4 v[182:185], v[130:131], off offset:512
	global_load_dwordx4 v[178:181], v[130:131], off offset:576
	v_or_b32_e32 v130, 32, v122
	v_or_b32_e32 v122, 48, v122
	v_ashrrev_i32_e32 v131, 31, v130
	v_ashrrev_i32_e32 v123, 31, v122
	v_lshlrev_b64 v[130:131], 12, v[130:131]
	v_lshlrev_b64 v[122:123], 12, v[122:123]
	v_lshl_add_u64 v[130:131], v[216:217], 0, v[130:131]
	v_lshl_add_u64 v[122:123], v[216:217], 0, v[122:123]
	global_load_dwordx4 v[174:177], v[130:131], off
	global_load_dwordx4 v[170:173], v[130:131], off offset:64
	global_load_dwordx4 v[166:169], v[130:131], off offset:512
	global_load_dwordx4 v[162:165], v[130:131], off offset:576
	global_load_dwordx4 v[158:161], v[122:123], off
	global_load_dwordx4 v[154:157], v[122:123], off offset:64
	global_load_dwordx4 v[150:153], v[122:123], off offset:512
	global_load_dwordx4 v[146:149], v[122:123], off offset:576
	v_lshl_add_u64 v[122:123], s[22:23], 0, v[124:125]
	global_load_dwordx4 v[142:145], v[122:123], off
	global_load_dwordx4 v[134:137], v[122:123], off offset:64
	global_load_dwordx4 v[130:133], v[122:123], off offset:512
	s_nop 0
	global_load_dwordx4 v[122:125], v[122:123], off offset:576
	v_mov_b32_e32 v238, s28
	v_add_u32_e32 v238, 0x80, v238
	v_or_b32_e32 v234, v238, v219
	v_add_u32_e32 v234, s30, v234
	v_ashrrev_i32_e32 v235, 31, v234
	v_lshlrev_b64 v[234:235], 12, v[234:235]
	v_lshl_add_u64 v[234:235], v[216:217], 0, v[234:235]
	v_mov_b32_e32 v238, 0x10000
	v_mov_b32_e32 v239, 0
	v_mul_f32_e32 v211, v139, v139
	v_mul_f32_e32 v212, v141, v141
	v_fmac_f32_e32 v211, v138, v138
	v_fmac_f32_e32 v212, v140, v140
	v_add_f32_e32 v211, v211, v212
	v_mul_f32_e32 v212, v127, v127
	v_mul_f32_e32 v213, v129, v129
	v_fmac_f32_e32 v212, v126, v126
	v_fmac_f32_e32 v213, v128, v128
	v_add_f32_e32 v212, v212, v213
	v_add_f32_e32 v211, v212, v211
	v_mul_f32_e32 v212, v119, v119
	v_mul_f32_e32 v213, v121, v121
	v_fmac_f32_e32 v212, v118, v118
	v_fmac_f32_e32 v213, v120, v120
	v_add_f32_e32 v212, v212, v213
	v_add_f32_e32 v211, v212, v211
	v_mul_f32_e32 v212, v115, v115
	v_mul_f32_e32 v213, v117, v117
	v_fmac_f32_e32 v212, v114, v114
	v_fmac_f32_e32 v213, v116, v116
	v_add_f32_e32 v212, v212, v213
	v_add_f32_e32 v211, v212, v211
	ds_bpermute_b32 v212, v1, v211
	v_and_b32_e32 v226, 63, v210
	s_lshl_b32 s0, s38, 2
	v_cmp_gt_u32_e64 s[4:5], 16, v226
	s_add_i32 s31, s0, 0
	s_waitcnt lgkmcnt(0)
	v_add_f32_e32 v211, v211, v212
	ds_bpermute_b32 v212, v233, v211
	s_and_saveexec_b64 s[0:1], s[4:5]
	s_cbranch_execz .LBB0_230
	s_lshl_b32 s2, s24, 10
	s_add_i32 s2, s31, s2
	v_lshl_add_u32 v213, v219, 4, s2
	s_waitcnt lgkmcnt(0)
	v_add_f32_e32 v211, v211, v212
	ds_write_b32 v213, v211
